# norm_rows: gain vector hoisted out of the row loop (4 quads loaded once), per-row vmcnt(0) waits behind stores dropped
# speedup vs baseline: 1.0737x; 1.0124x over previous
.LBB0_346:
	s_or_b64 exec, exec, s[2:3]
	s_waitcnt vmcnt(0) lgkmcnt(0)
	v_ashrrev_i32_e32 v2, 6, v4
	v_readlane_b32 s2, v253, 0
	s_mov_b32 s13, 0x8100
	s_barrier
	s_mov_b32 s14, 0x80ff
	v_lshl_add_u32 v180, s2, 3, v2
	v_cmp_gt_i32_e32 vcc, s13, v180
	s_and_saveexec_b64 s[8:9], vcc
	s_cbranch_execz .LBB0_356
	v_readlane_b32 s2, v253, 1
	v_readlane_b32 s3, v253, 2
	s_load_dword s4, s[2:3], 0x0
	v_and_b32_e32 v2, 64, v194
	v_add_u32_e32 v2, 64, v2
	v_xor_b32_e32 v3, 1, v194
	v_readlane_b32 s2, v255, 24
	s_waitcnt lgkmcnt(0)
	s_lshl_b32 s12, s4, 3
	v_cmp_lt_i32_e64 s[4:5], v3, v2
	s_lshl_b32 s2, s2, 10
	v_and_b32_e32 v130, 63, v4
	v_cndmask_b32_e64 v3, v194, v3, s[4:5]
	v_lshlrev_b32_e32 v198, 2, v3
	v_xor_b32_e32 v3, 2, v194
	v_cmp_lt_i32_e64 s[4:5], v3, v2
	s_ashr_i32 s3, s2, 31
	v_lshl_add_u64 v[0:1], s[2:3], 2, v[0:1]
	v_cndmask_b32_e64 v3, v194, v3, s[4:5]
	v_lshlrev_b32_e32 v199, 2, v3
	v_xor_b32_e32 v3, 4, v194
	v_cmp_lt_i32_e64 s[4:5], v3, v2
	v_lshlrev_b32_e32 v162, 4, v130
	v_lshl_add_u32 v124, v130, 7, v195
	v_cndmask_b32_e64 v3, v194, v3, s[4:5]
	v_lshlrev_b32_e32 v200, 2, v3
	v_xor_b32_e32 v3, 8, v194
	v_cmp_lt_i32_e64 s[4:5], v3, v2
	v_lshl_add_u64 v[172:173], v[0:1], 0, v[162:163]
	s_mov_b64 s[2:3], 0x1e320000
	v_cndmask_b32_e64 v3, v194, v3, s[4:5]
	v_lshlrev_b32_e32 v201, 2, v3
	v_xor_b32_e32 v3, 16, v194
	v_cmp_lt_i32_e64 s[4:5], v3, v2
	v_lshl_add_u64 v[174:175], v[128:129], 0, v[162:163]
	v_lshlrev_b32_e32 v162, 3, v130
	v_cndmask_b32_e64 v3, v194, v3, s[4:5]
	v_lshlrev_b32_e32 v202, 2, v3
	v_xor_b32_e32 v3, 32, v194
	v_cmp_lt_i32_e64 s[4:5], v3, v2
	v_lshl_add_u64 v[170:171], v[128:129], 0, s[2:3]
	v_lshl_add_u64 v[128:129], v[128:129], 0, v[162:163]
	v_cndmask_b32_e64 v2, v194, v3, s[4:5]
	v_lshlrev_b32_e32 v203, 2, v2
	ds_read_b128 v[0:3], v124
	ds_read_b128 v[4:7], v124 offset:16
	ds_read_b128 v[8:11], v124 offset:32
	ds_read_b128 v[12:15], v124 offset:48
	ds_read_b128 v[16:19], v124 offset:64
	ds_read_b128 v[20:23], v124 offset:80
	ds_read_b128 v[24:27], v124 offset:96
	ds_read_b128 v[28:31], v124 offset:112
	ds_read_b128 v[32:35], v124 offset:8192
	ds_read_b128 v[36:39], v124 offset:8208
	ds_read_b128 v[40:43], v124 offset:8224
	ds_read_b128 v[44:47], v124 offset:8240
	ds_read_b128 v[48:51], v124 offset:8256
	ds_read_b128 v[52:55], v124 offset:8272
	ds_read_b128 v[56:59], v124 offset:8288
	ds_read_b128 v[60:63], v124 offset:8304
	ds_read_b128 v[64:67], v124 offset:16384
	ds_read_b128 v[68:71], v124 offset:16400
	ds_read_b128 v[72:75], v124 offset:16416
	ds_read_b128 v[76:79], v124 offset:16432
	ds_read_b128 v[80:83], v124 offset:16448
	ds_read_b128 v[84:87], v124 offset:16464
	ds_read_b128 v[88:91], v124 offset:16480
	ds_read_b128 v[92:95], v124 offset:16496
	ds_read_b128 v[96:99], v124 offset:24576
	ds_read_b128 v[100:103], v124 offset:24592
	ds_read_b128 v[104:107], v124 offset:24608
	ds_read_b128 v[108:111], v124 offset:24624
	ds_read_b128 v[112:115], v124 offset:24640
	ds_read_b128 v[116:119], v124 offset:24656
	ds_read_b128 v[120:123], v124 offset:24672
	ds_read_b128 v[124:127], v124 offset:24688
	s_mov_b64 s[2:3], 0x8100000
	v_cmp_eq_u32_e32 vcc, 0, v130
	v_lshl_add_u64 v[176:177], v[128:129], 0, s[2:3]
	s_mov_b64 s[10:11], 0
	global_load_dwordx4 v[204:207], v[172:173], off
	global_load_dwordx4 v[208:211], v[172:173], off offset:1024
	global_load_dwordx4 v[212:215], v[172:173], off offset:2048
	global_load_dwordx4 v[216:219], v[172:173], off offset:3072
	s_waitcnt vmcnt(0)
	s_branch .LBB0_349

.LBB0_351:
	s_or_b64 exec, exec, s[2:3]
	s_waitcnt vmcnt(3)
	v_mov_b32_e32 v166, v157
	s_waitcnt vmcnt(2)
	v_mov_b32_e32 v167, v153
	v_mov_b32_e32 v164, v156
	v_mov_b32_e32 v165, v152
	v_pk_mul_f32 v[166:167], v[166:167], v[166:167]
	s_waitcnt vmcnt(1)
	v_mov_b32_e32 v182, v149
	v_pk_fma_f32 v[164:165], v[164:165], v[164:165], v[166:167]
	v_mov_b32_e32 v166, v158
	v_mov_b32_e32 v167, v154
	v_pk_fma_f32 v[164:165], v[166:167], v[166:167], v[164:165]
	v_mov_b32_e32 v166, v159
	v_mov_b32_e32 v167, v155
	s_waitcnt vmcnt(0)
	v_mov_b32_e32 v183, v145
	v_pk_fma_f32 v[164:165], v[166:167], v[166:167], v[164:165]
	v_mov_b32_e32 v166, v148
	v_mov_b32_e32 v167, v144
	v_pk_mul_f32 v[182:183], v[182:183], v[182:183]
	v_add_f32_e32 v162, v164, v165
	v_pk_fma_f32 v[166:167], v[166:167], v[166:167], v[182:183]
	v_mov_b32_e32 v182, v150
	v_mov_b32_e32 v183, v146
	v_pk_fma_f32 v[166:167], v[182:183], v[182:183], v[166:167]
	v_mov_b32_e32 v182, v151
	v_mov_b32_e32 v183, v147
	v_pk_fma_f32 v[166:167], v[182:183], v[182:183], v[166:167]
	v_lshlrev_b64 v[182:183], 11, v[180:181]
	v_add_f32_e32 v162, v162, v166
	v_add_f32_e32 v162, v162, v167
	ds_bpermute_b32 v164, v198, v162
	v_lshl_add_u64 v[186:187], v[176:177], 0, v[182:183]
	s_waitcnt lgkmcnt(0)
	v_add_f32_e32 v162, v162, v164
	ds_bpermute_b32 v164, v199, v162
	s_waitcnt lgkmcnt(0)
	v_add_f32_e32 v162, v162, v164
	ds_bpermute_b32 v164, v200, v162
	s_waitcnt lgkmcnt(0)
	v_add_f32_e32 v162, v162, v164
	ds_bpermute_b32 v164, v201, v162
	s_waitcnt lgkmcnt(0)
	v_add_f32_e32 v162, v162, v164
	ds_bpermute_b32 v164, v202, v162
	s_waitcnt lgkmcnt(0)
	v_add_f32_e32 v162, v162, v164
	ds_bpermute_b32 v164, v203, v162
	s_waitcnt lgkmcnt(0)
	v_add_f32_e32 v162, v162, v164
	v_fmamk_f32 v162, v162, 0x3a800000, v252
	v_cmp_gt_f32_e64 s[6:7], s90, v162
	v_mul_f32_e32 v164, 0x4b800000, v162
	s_nop 0
	v_cndmask_b32_e64 v162, v162, v164, s[6:7]
	v_rsq_f32_e32 v162, v162
	s_nop 0
	v_mul_f32_e32 v164, 0x45800000, v162
	v_cndmask_b32_e64 v162, v162, v164, s[6:7]
	s_nop 1
	v_mov_b32_e32 v164, v204
	v_mov_b32_e32 v165, v205
	v_mov_b32_e32 v166, v206
	v_mov_b32_e32 v167, v207
	v_pk_mul_f32 v[158:159], v[158:159], v[166:167]
	v_pk_mul_f32 v[164:165], v[156:157], v[164:165]
	v_pk_mul_f32 v[156:157], v[158:159], v[162:163] op_sel_hi:[1,0]
	v_pk_mul_f32 v[184:185], v[164:165], v[162:163] op_sel_hi:[1,0]
	v_cvt_pk_bf16_f32 v159, v156, v157
	v_cvt_pk_bf16_f32 v158, v184, v185
	global_store_dwordx2 v[186:187], v[158:159], off
	s_nop 1
	v_mov_b32_e32 v164, v208
	v_mov_b32_e32 v165, v209
	v_mov_b32_e32 v166, v210
	v_mov_b32_e32 v167, v211
	v_pk_mul_f32 v[154:155], v[154:155], v[166:167]
	v_pk_mul_f32 v[152:153], v[152:153], v[164:165]
	v_pk_mul_f32 v[164:165], v[154:155], v[162:163] op_sel_hi:[1,0]
	v_pk_mul_f32 v[166:167], v[152:153], v[162:163] op_sel_hi:[1,0]
	v_cvt_pk_bf16_f32 v153, v164, v165
	v_cvt_pk_bf16_f32 v152, v166, v167
	global_store_dwordx2 v[186:187], v[152:153], off offset:512
	s_nop 1
	v_mov_b32_e32 v152, v212
	v_mov_b32_e32 v153, v213
	v_mov_b32_e32 v154, v214
	v_mov_b32_e32 v155, v215
	v_pk_mul_f32 v[150:151], v[150:151], v[154:155]
	v_pk_mul_f32 v[152:153], v[148:149], v[152:153]
	v_pk_mul_f32 v[148:149], v[150:151], v[162:163] op_sel_hi:[1,0]
	v_pk_mul_f32 v[150:151], v[152:153], v[162:163] op_sel_hi:[1,0]
	v_cvt_pk_bf16_f32 v153, v148, v149
	v_cvt_pk_bf16_f32 v152, v150, v151
	global_store_dwordx2 v[186:187], v[152:153], off offset:1024
	v_pk_fma_f32 v[152:153], v[0:1], v[184:185], 0 op_sel_hi:[1,0,0]
	v_pk_fma_f32 v[154:155], v[6:7], v[184:185], 0 op_sel_hi:[1,0,0]
	v_pk_fma_f32 v[152:153], v[8:9], v[184:185], v[152:153] op_sel:[0,1,0]
	v_pk_fma_f32 v[154:155], v[14:15], v[184:185], v[154:155] op_sel:[0,1,0]
	v_pk_fma_f32 v[152:153], v[16:17], v[156:157], v[152:153] op_sel_hi:[1,0,1]
	v_pk_fma_f32 v[154:155], v[22:23], v[156:157], v[154:155] op_sel_hi:[1,0,1]
	v_pk_fma_f32 v[152:153], v[24:25], v[156:157], v[152:153] op_sel:[0,1,0]
	v_pk_fma_f32 v[154:155], v[30:31], v[156:157], v[154:155] op_sel:[0,1,0]
	v_pk_fma_f32 v[152:153], v[32:33], v[166:167], v[152:153] op_sel_hi:[1,0,1]
	v_pk_fma_f32 v[154:155], v[38:39], v[166:167], v[154:155] op_sel_hi:[1,0,1]
	v_pk_fma_f32 v[152:153], v[40:41], v[166:167], v[152:153] op_sel:[0,1,0]
	v_pk_fma_f32 v[154:155], v[46:47], v[166:167], v[154:155] op_sel:[0,1,0]
	v_pk_fma_f32 v[152:153], v[48:49], v[164:165], v[152:153] op_sel_hi:[1,0,1]
	v_pk_fma_f32 v[154:155], v[54:55], v[164:165], v[154:155] op_sel_hi:[1,0,1]
	v_pk_fma_f32 v[152:153], v[56:57], v[164:165], v[152:153] op_sel:[0,1,0]
	v_pk_fma_f32 v[154:155], v[62:63], v[164:165], v[154:155] op_sel:[0,1,0]
	v_pk_fma_f32 v[152:153], v[64:65], v[150:151], v[152:153] op_sel_hi:[1,0,1]
	v_pk_fma_f32 v[154:155], v[70:71], v[150:151], v[154:155] op_sel_hi:[1,0,1]
	v_pk_fma_f32 v[152:153], v[72:73], v[150:151], v[152:153] op_sel:[0,1,0]
	s_nop 0
	v_pk_fma_f32 v[182:183], v[80:81], v[148:149], v[152:153] op_sel_hi:[1,0,1]
	v_pk_fma_f32 v[152:153], v[2:3], v[184:185], 0 op_sel_hi:[1,0,0]
	s_nop 0
	v_pk_fma_f32 v[152:153], v[10:11], v[184:185], v[152:153] op_sel:[0,1,0]
	s_nop 0
	v_pk_fma_f32 v[152:153], v[18:19], v[156:157], v[152:153] op_sel_hi:[1,0,1]
	s_nop 0
	v_pk_fma_f32 v[152:153], v[26:27], v[156:157], v[152:153] op_sel:[0,1,0]
	s_nop 0
	v_pk_fma_f32 v[152:153], v[34:35], v[166:167], v[152:153] op_sel_hi:[1,0,1]
	s_nop 0
	v_pk_fma_f32 v[152:153], v[42:43], v[166:167], v[152:153] op_sel:[0,1,0]
	s_nop 0
	v_pk_fma_f32 v[152:153], v[50:51], v[164:165], v[152:153] op_sel_hi:[1,0,1]
	s_nop 0
	v_pk_fma_f32 v[152:153], v[58:59], v[164:165], v[152:153] op_sel:[0,1,0]
	s_nop 0
	v_pk_fma_f32 v[152:153], v[66:67], v[150:151], v[152:153] op_sel_hi:[1,0,1]
	s_nop 0
	v_pk_fma_f32 v[152:153], v[74:75], v[150:151], v[152:153] op_sel:[0,1,0]
	s_nop 0
	v_pk_fma_f32 v[158:159], v[82:83], v[148:149], v[152:153] op_sel_hi:[1,0,1]
	v_pk_fma_f32 v[152:153], v[4:5], v[184:185], 0 op_sel_hi:[1,0,0]
	v_pk_fma_f32 v[158:159], v[90:91], v[148:149], v[158:159] op_sel:[0,1,0]
	v_pk_fma_f32 v[152:153], v[12:13], v[184:185], v[152:153] op_sel:[0,1,0]
	s_nop 0
	v_pk_fma_f32 v[152:153], v[20:21], v[156:157], v[152:153] op_sel_hi:[1,0,1]
	s_nop 0
	v_pk_fma_f32 v[152:153], v[28:29], v[156:157], v[152:153] op_sel:[0,1,0]
	s_nop 0
	v_pk_fma_f32 v[152:153], v[36:37], v[166:167], v[152:153] op_sel_hi:[1,0,1]
	s_nop 0
	v_pk_fma_f32 v[152:153], v[44:45], v[166:167], v[152:153] op_sel:[0,1,0]
	s_nop 0
	v_pk_fma_f32 v[152:153], v[52:53], v[164:165], v[152:153] op_sel_hi:[1,0,1]
	s_nop 0
	v_pk_fma_f32 v[152:153], v[60:61], v[164:165], v[152:153] op_sel:[0,1,0]
	s_nop 0
	v_pk_fma_f32 v[152:153], v[68:69], v[150:151], v[152:153] op_sel_hi:[1,0,1]
	s_nop 0
	v_pk_fma_f32 v[152:153], v[76:77], v[150:151], v[152:153] op_sel:[0,1,0]
	v_pk_fma_f32 v[150:151], v[78:79], v[150:151], v[154:155] op_sel:[0,1,0]
	s_nop 1
	v_mov_b32_e32 v154, v216
	v_mov_b32_e32 v155, v217
	v_mov_b32_e32 v156, v218
	v_mov_b32_e32 v157, v219
	v_pk_fma_f32 v[152:153], v[84:85], v[148:149], v[152:153] op_sel_hi:[1,0,1]
	v_pk_fma_f32 v[150:151], v[86:87], v[148:149], v[150:151] op_sel_hi:[1,0,1]
	v_pk_fma_f32 v[152:153], v[92:93], v[148:149], v[152:153] op_sel:[0,1,0]
	v_pk_mul_f32 v[144:145], v[144:145], v[154:155]
	v_pk_mul_f32 v[146:147], v[146:147], v[156:157]
	v_pk_mul_f32 v[156:157], v[144:145], v[162:163] op_sel_hi:[1,0]
	v_pk_mul_f32 v[154:155], v[146:147], v[162:163] op_sel_hi:[1,0]
	v_pk_fma_f32 v[158:159], v[98:99], v[156:157], v[158:159] op_sel_hi:[1,0,1]
	v_cvt_pk_bf16_f32 v144, v156, v157
	v_pk_fma_f32 v[158:159], v[156:157], v[106:107], v[158:159] op_sel:[1,0,0]
	v_cvt_pk_bf16_f32 v145, v154, v155
	v_pk_fma_f32 v[158:159], v[154:155], v[114:115], v[158:159] op_sel_hi:[0,1,1]
	v_pk_fma_f32 v[158:159], v[154:155], v[122:123], v[158:159] op_sel:[1,0,0]
	ds_bpermute_b32 v164, v198, v158
	ds_bpermute_b32 v165, v198, v159
	global_store_dwordx2 v[186:187], v[144:145], off offset:1536
	v_pk_fma_f32 v[144:145], v[88:89], v[148:149], v[182:183] op_sel:[0,1,0]
	v_pk_fma_f32 v[148:149], v[94:95], v[148:149], v[150:151] op_sel:[0,1,0]
	v_pk_fma_f32 v[144:145], v[96:97], v[156:157], v[144:145] op_sel_hi:[1,0,1]
	s_waitcnt lgkmcnt(0)
	v_pk_add_f32 v[158:159], v[158:159], v[164:165]
	ds_bpermute_b32 v164, v199, v158
	ds_bpermute_b32 v165, v199, v159
	v_pk_fma_f32 v[152:153], v[156:157], v[100:101], v[152:153] op_sel_hi:[0,1,1]
	v_pk_fma_f32 v[148:149], v[156:157], v[102:103], v[148:149] op_sel_hi:[0,1,1]
	v_pk_fma_f32 v[144:145], v[156:157], v[104:105], v[144:145] op_sel:[1,0,0]
	v_pk_fma_f32 v[152:153], v[156:157], v[108:109], v[152:153] op_sel:[1,0,0]
	s_waitcnt lgkmcnt(0)
	v_pk_add_f32 v[158:159], v[158:159], v[164:165]
	ds_bpermute_b32 v164, v200, v158
	ds_bpermute_b32 v165, v200, v159
	v_pk_fma_f32 v[148:149], v[156:157], v[110:111], v[148:149] op_sel:[1,0,0]
	v_pk_fma_f32 v[144:145], v[154:155], v[112:113], v[144:145] op_sel_hi:[0,1,1]
	v_pk_fma_f32 v[152:153], v[154:155], v[116:117], v[152:153] op_sel_hi:[0,1,1]
	v_pk_fma_f32 v[148:149], v[154:155], v[118:119], v[148:149] op_sel_hi:[0,1,1]
	s_waitcnt lgkmcnt(0)
	v_pk_add_f32 v[158:159], v[158:159], v[164:165]
	ds_bpermute_b32 v164, v201, v158
	ds_bpermute_b32 v165, v201, v159
	v_pk_fma_f32 v[144:145], v[154:155], v[120:121], v[144:145] op_sel:[1,0,0]
	v_pk_fma_f32 v[152:153], v[154:155], v[124:125], v[152:153] op_sel:[1,0,0]
	v_pk_fma_f32 v[148:149], v[154:155], v[126:127], v[148:149] op_sel:[1,0,0]
	ds_bpermute_b32 v146, v198, v144
	s_waitcnt lgkmcnt(1)
	v_pk_add_f32 v[158:159], v[158:159], v[164:165]
	ds_bpermute_b32 v164, v202, v158
	ds_bpermute_b32 v165, v202, v159
	ds_bpermute_b32 v147, v198, v145
	ds_bpermute_b32 v150, v198, v148
	ds_bpermute_b32 v151, v198, v149
	s_waitcnt lgkmcnt(3)
	v_pk_add_f32 v[158:159], v[158:159], v[164:165]
	ds_bpermute_b32 v164, v198, v152
	ds_bpermute_b32 v165, v198, v153
	s_waitcnt lgkmcnt(4)
	v_pk_add_f32 v[144:145], v[144:145], v[146:147]
	s_waitcnt lgkmcnt(2)
	v_pk_add_f32 v[148:149], v[148:149], v[150:151]
	ds_bpermute_b32 v146, v199, v144
	ds_bpermute_b32 v147, v199, v145
	s_waitcnt lgkmcnt(2)
	v_pk_add_f32 v[152:153], v[152:153], v[164:165]
	ds_bpermute_b32 v164, v199, v152
	ds_bpermute_b32 v165, v199, v153
	ds_bpermute_b32 v150, v199, v148
	ds_bpermute_b32 v151, v199, v149
	s_waitcnt lgkmcnt(4)
	v_pk_add_f32 v[144:145], v[144:145], v[146:147]
	ds_bpermute_b32 v146, v200, v144
	s_waitcnt lgkmcnt(3)
	v_pk_add_f32 v[152:153], v[152:153], v[164:165]
	ds_bpermute_b32 v147, v200, v145
	s_waitcnt lgkmcnt(2)
	v_pk_add_f32 v[148:149], v[148:149], v[150:151]
	ds_bpermute_b32 v164, v200, v152
	ds_bpermute_b32 v165, v200, v153
	ds_bpermute_b32 v150, v200, v148
	ds_bpermute_b32 v151, v200, v149
	s_waitcnt lgkmcnt(4)
	v_pk_add_f32 v[144:145], v[144:145], v[146:147]
	ds_bpermute_b32 v146, v201, v144
	s_waitcnt lgkmcnt(3)
	v_pk_add_f32 v[152:153], v[152:153], v[164:165]
	ds_bpermute_b32 v147, v201, v145
	s_waitcnt lgkmcnt(2)
	v_pk_add_f32 v[148:149], v[148:149], v[150:151]
	ds_bpermute_b32 v164, v201, v152
	ds_bpermute_b32 v165, v201, v153
	ds_bpermute_b32 v150, v201, v148
	ds_bpermute_b32 v151, v201, v149
	s_waitcnt lgkmcnt(4)
	v_pk_add_f32 v[144:145], v[144:145], v[146:147]
	ds_bpermute_b32 v146, v202, v144
	s_waitcnt lgkmcnt(3)
	v_pk_add_f32 v[152:153], v[152:153], v[164:165]
	ds_bpermute_b32 v147, v202, v145
	s_waitcnt lgkmcnt(2)
	v_pk_add_f32 v[148:149], v[148:149], v[150:151]
	ds_bpermute_b32 v164, v202, v152
	ds_bpermute_b32 v165, v202, v153
	ds_bpermute_b32 v150, v202, v148
	ds_bpermute_b32 v151, v202, v149
	s_waitcnt lgkmcnt(4)
	v_pk_add_f32 v[144:145], v[144:145], v[146:147]
	ds_bpermute_b32 v146, v203, v144
	s_waitcnt lgkmcnt(3)
	v_pk_add_f32 v[152:153], v[152:153], v[164:165]
	ds_bpermute_b32 v147, v203, v145
	s_waitcnt lgkmcnt(2)
	v_pk_add_f32 v[148:149], v[148:149], v[150:151]
	ds_bpermute_b32 v182, v203, v158
	ds_bpermute_b32 v183, v203, v159
	ds_bpermute_b32 v184, v203, v152
	ds_bpermute_b32 v185, v203, v153
	ds_bpermute_b32 v150, v203, v148
	ds_bpermute_b32 v151, v203, v149
	s_and_saveexec_b64 s[2:3], vcc
	s_cbranch_execz .LBB0_353
	v_lshlrev_b64 v[154:155], 5, v[180:181]
	v_lshl_add_u64 v[154:155], v[170:171], 0, v[154:155]
	s_waitcnt lgkmcnt(6)
	v_pk_add_f32 v[144:145], v[144:145], v[146:147]
	s_waitcnt lgkmcnt(4)
	v_pk_add_f32 v[146:147], v[158:159], v[182:183]
	global_store_dwordx4 v[154:155], v[144:147], off
	s_waitcnt lgkmcnt(2)
	s_nop 0
	v_pk_add_f32 v[144:145], v[152:153], v[184:185]
	s_waitcnt lgkmcnt(0)
	v_pk_add_f32 v[146:147], v[148:149], v[150:151]
	global_store_dwordx4 v[154:155], v[144:147], off offset:16
.LBB0_353:
	s_or_b64 exec, exec, s[2:3]
	s_and_saveexec_b64 s[2:3], s[4:5]
	s_cbranch_execz .LBB0_348
	s_waitcnt lgkmcnt(0)
	s_nop 1
	v_mov_b32_e32 v150, v204
	v_mov_b32_e32 v151, v205
	v_mov_b32_e32 v152, v206
	v_mov_b32_e32 v153, v207
	v_mov_b32_e32 v146, v137
	v_mov_b32_e32 v147, v141
	v_mov_b32_e32 v144, v136
	v_mov_b32_e32 v145, v140
	v_pk_mul_f32 v[146:147], v[146:147], v[146:147]
	v_mov_b32_e32 v148, v129
	v_pk_fma_f32 v[144:145], v[144:145], v[144:145], v[146:147]
	v_mov_b32_e32 v146, v138
	v_mov_b32_e32 v147, v142
	v_pk_fma_f32 v[144:145], v[146:147], v[146:147], v[144:145]
	v_mov_b32_e32 v146, v139
	v_mov_b32_e32 v147, v143
	v_mov_b32_e32 v149, v133
	v_pk_fma_f32 v[144:145], v[146:147], v[146:147], v[144:145]
	v_mov_b32_e32 v146, v128
	v_mov_b32_e32 v147, v132
	v_pk_mul_f32 v[148:149], v[148:149], v[148:149]
	v_add_f32_e32 v144, v144, v145
	v_pk_fma_f32 v[146:147], v[146:147], v[146:147], v[148:149]
	v_mov_b32_e32 v148, v130
	v_mov_b32_e32 v149, v134
	v_pk_fma_f32 v[146:147], v[148:149], v[148:149], v[146:147]
	v_mov_b32_e32 v148, v131
	v_mov_b32_e32 v149, v135
	v_pk_fma_f32 v[146:147], v[148:149], v[148:149], v[146:147]
	v_pk_mul_f32 v[150:151], v[140:141], v[150:151]
	v_add_f32_e32 v144, v147, v144
	v_add_f32_e32 v144, v146, v144
	ds_bpermute_b32 v145, v198, v144
	v_pk_mul_f32 v[146:147], v[142:143], v[152:153]
	s_waitcnt lgkmcnt(0)
	v_add_f32_e32 v144, v144, v145
	ds_bpermute_b32 v145, v199, v144
	s_waitcnt lgkmcnt(0)
	v_add_f32_e32 v144, v144, v145
	ds_bpermute_b32 v145, v200, v144
	s_waitcnt lgkmcnt(0)
	v_add_f32_e32 v144, v144, v145
	ds_bpermute_b32 v145, v201, v144
	s_waitcnt lgkmcnt(0)
	v_add_f32_e32 v144, v144, v145
	ds_bpermute_b32 v145, v202, v144
	s_waitcnt lgkmcnt(0)
	v_add_f32_e32 v144, v144, v145
	ds_bpermute_b32 v145, v203, v144
	s_waitcnt lgkmcnt(0)
	v_add_f32_e32 v144, v144, v145
	v_fmamk_f32 v144, v144, 0x3a800000, v252
	v_cmp_gt_f32_e64 s[4:5], s90, v144
	v_mul_f32_e32 v145, 0x4b800000, v144
	s_nop 0
	v_cndmask_b32_e64 v144, v144, v145, s[4:5]
	v_rsq_f32_e32 v144, v144
	s_nop 0
	v_mul_f32_e32 v145, 0x45800000, v144
	v_cndmask_b32_e64 v148, v144, v145, s[4:5]
	v_lshlrev_b64 v[144:145], 11, v[178:179]
	v_pk_mul_f32 v[146:147], v[146:147], v[148:149] op_sel_hi:[1,0]
	v_pk_mul_f32 v[154:155], v[150:151], v[148:149] op_sel_hi:[1,0]
	v_cvt_pk_bf16_f32 v151, v146, v147
	v_cvt_pk_bf16_f32 v150, v154, v155
	v_lshl_add_u64 v[180:181], v[176:177], 0, v[144:145]
	global_store_dwordx2 v[180:181], v[150:151], off
	s_nop 1
	v_mov_b32_e32 v150, v208
	v_mov_b32_e32 v151, v209
	v_mov_b32_e32 v152, v210
	v_mov_b32_e32 v153, v211
	v_pk_fma_f32 v[182:183], v[6:7], v[154:155], 0 op_sel_hi:[1,0,0]
	v_pk_mul_f32 v[144:145], v[138:139], v[152:153]
	v_pk_mul_f32 v[150:151], v[136:137], v[150:151]
	v_pk_mul_f32 v[156:157], v[144:145], v[148:149] op_sel_hi:[1,0]
	v_pk_mul_f32 v[164:165], v[150:151], v[148:149] op_sel_hi:[1,0]
	v_cvt_pk_bf16_f32 v145, v156, v157
	v_cvt_pk_bf16_f32 v144, v164, v165
	global_store_dwordx2 v[180:181], v[144:145], off offset:512
	s_nop 1
	v_mov_b32_e32 v150, v212
	v_mov_b32_e32 v151, v213
	v_mov_b32_e32 v152, v214
	v_mov_b32_e32 v153, v215
	v_pk_mul_f32 v[144:145], v[134:135], v[152:153]
	v_pk_fma_f32 v[152:153], v[2:3], v[154:155], 0 op_sel_hi:[1,0,0]
	v_pk_mul_f32 v[150:151], v[132:133], v[150:151]
	v_pk_fma_f32 v[152:153], v[10:11], v[154:155], v[152:153] op_sel:[0,1,0]
	v_pk_mul_f32 v[166:167], v[150:151], v[148:149] op_sel_hi:[1,0]
	v_pk_fma_f32 v[152:153], v[18:19], v[146:147], v[152:153] op_sel_hi:[1,0,1]
	v_pk_mul_f32 v[144:145], v[144:145], v[148:149] op_sel_hi:[1,0]
	v_pk_fma_f32 v[152:153], v[26:27], v[146:147], v[152:153] op_sel:[0,1,0]
	v_cvt_pk_bf16_f32 v150, v166, v167
	v_pk_fma_f32 v[152:153], v[34:35], v[164:165], v[152:153] op_sel_hi:[1,0,1]
	v_cvt_pk_bf16_f32 v151, v144, v145
	v_pk_fma_f32 v[152:153], v[42:43], v[164:165], v[152:153] op_sel:[0,1,0]
	global_store_dwordx2 v[180:181], v[150:151], off offset:1024
	v_pk_fma_f32 v[152:153], v[50:51], v[156:157], v[152:153] op_sel_hi:[1,0,1]
	v_pk_fma_f32 v[150:151], v[0:1], v[154:155], 0 op_sel_hi:[1,0,0]
	v_pk_fma_f32 v[152:153], v[58:59], v[156:157], v[152:153] op_sel:[0,1,0]
	v_pk_fma_f32 v[150:151], v[8:9], v[154:155], v[150:151] op_sel:[0,1,0]
	v_pk_fma_f32 v[152:153], v[66:67], v[166:167], v[152:153] op_sel_hi:[1,0,1]
	v_pk_fma_f32 v[150:151], v[16:17], v[146:147], v[150:151] op_sel_hi:[1,0,1]
	v_pk_fma_f32 v[152:153], v[74:75], v[166:167], v[152:153] op_sel:[0,1,0]
	v_pk_fma_f32 v[150:151], v[24:25], v[146:147], v[150:151] op_sel:[0,1,0]
	v_pk_fma_f32 v[158:159], v[82:83], v[144:145], v[152:153] op_sel_hi:[1,0,1]
	v_pk_fma_f32 v[152:153], v[4:5], v[154:155], 0 op_sel_hi:[1,0,0]
	v_pk_fma_f32 v[150:151], v[32:33], v[164:165], v[150:151] op_sel_hi:[1,0,1]
	v_pk_fma_f32 v[152:153], v[12:13], v[154:155], v[152:153] op_sel:[0,1,0]
	v_pk_fma_f32 v[154:155], v[14:15], v[154:155], v[182:183] op_sel:[0,1,0]
	v_pk_fma_f32 v[152:153], v[20:21], v[146:147], v[152:153] op_sel_hi:[1,0,1]
	v_pk_fma_f32 v[154:155], v[22:23], v[146:147], v[154:155] op_sel_hi:[1,0,1]
	v_pk_fma_f32 v[152:153], v[28:29], v[146:147], v[152:153] op_sel:[0,1,0]
	v_pk_fma_f32 v[146:147], v[30:31], v[146:147], v[154:155] op_sel:[0,1,0]
	v_pk_fma_f32 v[152:153], v[36:37], v[164:165], v[152:153] op_sel_hi:[1,0,1]
	v_pk_fma_f32 v[146:147], v[38:39], v[164:165], v[146:147] op_sel_hi:[1,0,1]
	v_pk_fma_f32 v[150:151], v[40:41], v[164:165], v[150:151] op_sel:[0,1,0]
	v_pk_fma_f32 v[152:153], v[44:45], v[164:165], v[152:153] op_sel:[0,1,0]
	v_pk_fma_f32 v[146:147], v[46:47], v[164:165], v[146:147] op_sel:[0,1,0]
	v_pk_fma_f32 v[150:151], v[48:49], v[156:157], v[150:151] op_sel_hi:[1,0,1]
	v_pk_fma_f32 v[152:153], v[52:53], v[156:157], v[152:153] op_sel_hi:[1,0,1]
	v_pk_fma_f32 v[146:147], v[54:55], v[156:157], v[146:147] op_sel_hi:[1,0,1]
	v_pk_fma_f32 v[150:151], v[56:57], v[156:157], v[150:151] op_sel:[0,1,0]
	v_pk_fma_f32 v[152:153], v[60:61], v[156:157], v[152:153] op_sel:[0,1,0]
	v_pk_fma_f32 v[146:147], v[62:63], v[156:157], v[146:147] op_sel:[0,1,0]
	s_nop 1
	v_mov_b32_e32 v154, v216
	v_mov_b32_e32 v155, v217
	v_mov_b32_e32 v156, v218
	v_mov_b32_e32 v157, v219
	v_pk_fma_f32 v[158:159], v[90:91], v[144:145], v[158:159] op_sel:[0,1,0]
	v_pk_fma_f32 v[150:151], v[64:65], v[166:167], v[150:151] op_sel_hi:[1,0,1]
	v_pk_fma_f32 v[152:153], v[68:69], v[166:167], v[152:153] op_sel_hi:[1,0,1]
	v_pk_fma_f32 v[146:147], v[70:71], v[166:167], v[146:147] op_sel_hi:[1,0,1]
	v_pk_fma_f32 v[150:151], v[72:73], v[166:167], v[150:151] op_sel:[0,1,0]
	v_pk_fma_f32 v[152:153], v[76:77], v[166:167], v[152:153] op_sel:[0,1,0]
	v_pk_fma_f32 v[146:147], v[78:79], v[166:167], v[146:147] op_sel:[0,1,0]
	v_pk_fma_f32 v[150:151], v[80:81], v[144:145], v[150:151] op_sel_hi:[1,0,1]
	v_pk_fma_f32 v[152:153], v[84:85], v[144:145], v[152:153] op_sel_hi:[1,0,1]
	v_pk_fma_f32 v[146:147], v[86:87], v[144:145], v[146:147] op_sel_hi:[1,0,1]
	v_pk_fma_f32 v[152:153], v[92:93], v[144:145], v[152:153] op_sel:[0,1,0]
	v_pk_mul_f32 v[156:157], v[130:131], v[156:157]
	v_pk_mul_f32 v[164:165], v[128:129], v[154:155]
	v_pk_mul_f32 v[154:155], v[156:157], v[148:149] op_sel_hi:[1,0]
	v_pk_mul_f32 v[156:157], v[164:165], v[148:149] op_sel_hi:[1,0]
	v_cvt_pk_bf16_f32 v149, v154, v155
	v_pk_fma_f32 v[158:159], v[98:99], v[156:157], v[158:159] op_sel_hi:[1,0,1]
	v_cvt_pk_bf16_f32 v148, v156, v157
	v_pk_fma_f32 v[158:159], v[106:107], v[156:157], v[158:159] op_sel:[0,1,0]
	global_store_dwordx2 v[180:181], v[148:149], off offset:1536
	v_pk_fma_f32 v[158:159], v[114:115], v[154:155], v[158:159] op_sel_hi:[1,0,1]
	v_pk_fma_f32 v[148:149], v[88:89], v[144:145], v[150:151] op_sel:[0,1,0]
	v_pk_fma_f32 v[158:159], v[122:123], v[154:155], v[158:159] op_sel:[0,1,0]
	ds_bpermute_b32 v164, v198, v158
	ds_bpermute_b32 v165, v198, v159
	v_pk_fma_f32 v[144:145], v[94:95], v[144:145], v[146:147] op_sel:[0,1,0]
	v_pk_fma_f32 v[148:149], v[96:97], v[156:157], v[148:149] op_sel_hi:[1,0,1]
	v_pk_fma_f32 v[152:153], v[100:101], v[156:157], v[152:153] op_sel_hi:[1,0,1]
	v_pk_fma_f32 v[144:145], v[102:103], v[156:157], v[144:145] op_sel_hi:[1,0,1]
	s_waitcnt lgkmcnt(0)
	v_pk_add_f32 v[158:159], v[158:159], v[164:165]
	ds_bpermute_b32 v164, v199, v158
	ds_bpermute_b32 v165, v199, v159
	v_pk_fma_f32 v[148:149], v[104:105], v[156:157], v[148:149] op_sel:[0,1,0]
	v_pk_fma_f32 v[152:153], v[108:109], v[156:157], v[152:153] op_sel:[0,1,0]
	v_pk_fma_f32 v[144:145], v[110:111], v[156:157], v[144:145] op_sel:[0,1,0]
	v_pk_fma_f32 v[148:149], v[112:113], v[154:155], v[148:149] op_sel_hi:[1,0,1]
	s_waitcnt lgkmcnt(0)
	v_pk_add_f32 v[158:159], v[158:159], v[164:165]
	ds_bpermute_b32 v164, v200, v158
	ds_bpermute_b32 v165, v200, v159
	v_pk_fma_f32 v[152:153], v[116:117], v[154:155], v[152:153] op_sel_hi:[1,0,1]
	v_pk_fma_f32 v[144:145], v[118:119], v[154:155], v[144:145] op_sel_hi:[1,0,1]
	v_pk_fma_f32 v[148:149], v[120:121], v[154:155], v[148:149] op_sel:[0,1,0]
	v_pk_fma_f32 v[152:153], v[124:125], v[154:155], v[152:153] op_sel:[0,1,0]
	s_waitcnt lgkmcnt(0)
	v_pk_add_f32 v[158:159], v[158:159], v[164:165]
	ds_bpermute_b32 v164, v201, v158
	ds_bpermute_b32 v165, v201, v159
	v_pk_fma_f32 v[144:145], v[126:127], v[154:155], v[144:145] op_sel:[0,1,0]
	ds_bpermute_b32 v150, v198, v148
	ds_bpermute_b32 v151, v198, v149
	ds_bpermute_b32 v146, v198, v144
	s_waitcnt lgkmcnt(3)
	v_pk_add_f32 v[158:159], v[158:159], v[164:165]
	ds_bpermute_b32 v164, v202, v158
	ds_bpermute_b32 v165, v202, v159
	ds_bpermute_b32 v147, v198, v145
	s_waitcnt lgkmcnt(4)
	v_pk_add_f32 v[148:149], v[148:149], v[150:151]
	ds_bpermute_b32 v150, v199, v148
	ds_bpermute_b32 v151, v199, v149
	s_waitcnt lgkmcnt(3)
	v_pk_add_f32 v[158:159], v[158:159], v[164:165]
	ds_bpermute_b32 v164, v198, v152
	ds_bpermute_b32 v165, v198, v153
	s_waitcnt lgkmcnt(4)
	v_pk_add_f32 v[144:145], v[144:145], v[146:147]
	ds_bpermute_b32 v146, v199, v144
	ds_bpermute_b32 v147, v199, v145
	s_waitcnt lgkmcnt(4)
	v_pk_add_f32 v[148:149], v[148:149], v[150:151]
	s_waitcnt lgkmcnt(2)
	v_pk_add_f32 v[152:153], v[152:153], v[164:165]
	ds_bpermute_b32 v164, v199, v152
	ds_bpermute_b32 v165, v199, v153
	s_waitcnt lgkmcnt(2)
	v_pk_add_f32 v[144:145], v[144:145], v[146:147]
	ds_bpermute_b32 v150, v200, v148
	ds_bpermute_b32 v151, v200, v149
	ds_bpermute_b32 v146, v200, v144
	s_waitcnt lgkmcnt(3)
	v_pk_add_f32 v[152:153], v[152:153], v[164:165]
	ds_bpermute_b32 v164, v200, v152
	ds_bpermute_b32 v165, v200, v153
	ds_bpermute_b32 v147, v200, v145
	s_waitcnt lgkmcnt(4)
	v_pk_add_f32 v[148:149], v[148:149], v[150:151]
	ds_bpermute_b32 v150, v201, v148
	ds_bpermute_b32 v151, v201, v149
	s_waitcnt lgkmcnt(3)
	v_pk_add_f32 v[152:153], v[152:153], v[164:165]
	s_waitcnt lgkmcnt(2)
	v_pk_add_f32 v[144:145], v[144:145], v[146:147]
	ds_bpermute_b32 v164, v201, v152
	ds_bpermute_b32 v165, v201, v153
	ds_bpermute_b32 v146, v201, v144
	ds_bpermute_b32 v147, v201, v145
	s_waitcnt lgkmcnt(4)
	v_pk_add_f32 v[148:149], v[148:149], v[150:151]
	ds_bpermute_b32 v150, v202, v148
	s_waitcnt lgkmcnt(3)
	v_pk_add_f32 v[152:153], v[152:153], v[164:165]
	ds_bpermute_b32 v151, v202, v149
	s_waitcnt lgkmcnt(2)
	v_pk_add_f32 v[144:145], v[144:145], v[146:147]
	ds_bpermute_b32 v164, v202, v152
	ds_bpermute_b32 v165, v202, v153
	ds_bpermute_b32 v146, v202, v144
	ds_bpermute_b32 v147, v202, v145
	s_waitcnt lgkmcnt(4)
	v_pk_add_f32 v[148:149], v[148:149], v[150:151]
	ds_bpermute_b32 v150, v203, v148
	s_waitcnt lgkmcnt(3)
	v_pk_add_f32 v[152:153], v[152:153], v[164:165]
	ds_bpermute_b32 v151, v203, v149
	s_waitcnt lgkmcnt(2)
	v_pk_add_f32 v[144:145], v[144:145], v[146:147]
	ds_bpermute_b32 v180, v203, v158
	ds_bpermute_b32 v181, v203, v159
	ds_bpermute_b32 v182, v203, v152
	ds_bpermute_b32 v183, v203, v153
	ds_bpermute_b32 v146, v203, v144
	ds_bpermute_b32 v147, v203, v145
	s_and_b64 exec, exec, vcc
	s_cbranch_execz .LBB0_348
	v_lshlrev_b64 v[154:155], 5, v[178:179]
	v_lshl_add_u64 v[154:155], v[170:171], 0, v[154:155]
	s_waitcnt lgkmcnt(6)
	v_pk_add_f32 v[148:149], v[148:149], v[150:151]
	s_waitcnt lgkmcnt(4)
	v_pk_add_f32 v[150:151], v[158:159], v[180:181]
	global_store_dwordx4 v[154:155], v[148:151], off
	s_waitcnt lgkmcnt(2)
	s_nop 0
	v_pk_add_f32 v[148:149], v[152:153], v[182:183]
	s_waitcnt lgkmcnt(0)
	v_pk_add_f32 v[150:151], v[144:145], v[146:147]
	global_store_dwordx4 v[154:155], v[148:151], off offset:16
	s_branch .LBB0_348

.LBB0_1692:
	s_andn2_b64 vcc, exec, s[2:3]
	s_cbranch_vccnz .LBB0_1758
	s_mov_b64 s[2:3], s[40:41]
	s_waitcnt vmcnt(0)
	v_mov_b32_e32 v4, v160
	s_waitcnt lgkmcnt(0)
	v_mov_b64_e32 v[2:3], s[2:3]
	flat_load_dwordx2 v[0:1], v[2:3] offset:248
	s_nop 0
	flat_load_dwordx2 v[2:3], v[2:3] offset:200
	v_readlane_b32 s2, v253, 0
	v_ashrrev_i32_e32 v5, 6, v4
	s_mov_b32 s9, 0x8100
	v_lshl_add_u32 v42, s2, 3, v5
	v_cmp_gt_i32_e32 vcc, s9, v42
	s_and_saveexec_b64 s[2:3], vcc
	s_mov_b32 s12, 0x80ff
	s_cbranch_execz .LBB0_1700
	v_and_b32_e32 v5, 64, v194
	v_add_u32_e32 v5, 64, v5
	v_xor_b32_e32 v6, 1, v194
	v_cmp_lt_i32_e32 vcc, v6, v5
	v_readlane_b32 s4, v253, 1
	v_readlane_b32 s5, v253, 2
	v_cndmask_b32_e32 v6, v194, v6, vcc
	v_lshlrev_b32_e32 v41, 2, v6
	v_xor_b32_e32 v6, 2, v194
	v_cmp_lt_i32_e32 vcc, v6, v5
	s_load_dword s6, s[4:5], 0x0
	v_readlane_b32 s4, v255, 24
	v_cndmask_b32_e32 v6, v194, v6, vcc
	v_lshlrev_b32_e32 v44, 2, v6
	v_xor_b32_e32 v6, 4, v194
	v_cmp_lt_i32_e32 vcc, v6, v5
	s_lshl_b32 s4, s4, 10
	v_lshlrev_b32_e32 v4, 2, v4
	v_cndmask_b32_e32 v6, v194, v6, vcc
	v_lshlrev_b32_e32 v45, 2, v6
	v_xor_b32_e32 v6, 8, v194
	v_cmp_lt_i32_e32 vcc, v6, v5
	s_ashr_i32 s5, s4, 31
	v_and_b32_e32 v4, 0xfc, v4
	v_cndmask_b32_e32 v6, v194, v6, vcc
	v_lshlrev_b32_e32 v46, 2, v6
	v_xor_b32_e32 v6, 16, v194
	v_cmp_lt_i32_e32 vcc, v6, v5
	s_waitcnt vmcnt(0) lgkmcnt(0)
	v_lshl_add_u64 v[2:3], s[4:5], 2, v[2:3]
	v_lshlrev_b32_e32 v162, 2, v4
	v_cndmask_b32_e32 v6, v194, v6, vcc
	v_lshlrev_b32_e32 v47, 2, v6
	v_xor_b32_e32 v6, 32, v194
	v_cmp_lt_i32_e32 vcc, v6, v5
	v_lshl_add_u64 v[32:33], v[2:3], 0, v[162:163]
	v_lshl_add_u64 v[34:35], v[0:1], 0, v[162:163]
	v_lshlrev_b32_e32 v162, 1, v4
	v_cndmask_b32_e32 v5, v194, v6, vcc
	v_lshl_add_u64 v[0:1], v[0:1], 0, v[162:163]
	s_mov_b64 s[4:5], 0x8100000
	s_lshl_b32 s8, s6, 3
	v_lshlrev_b32_e32 v48, 2, v5
	v_lshl_add_u64 v[36:37], v[0:1], 0, s[4:5]
	s_mov_b64 s[6:7], 0
	global_load_dwordx4 v[56:59], v[32:33], off
	global_load_dwordx4 v[60:63], v[32:33], off offset:1024
	global_load_dwordx4 v[64:67], v[32:33], off offset:2048
	global_load_dwordx4 v[68:71], v[32:33], off offset:3072
	s_waitcnt vmcnt(0)
	s_branch .LBB0_1696

.LBB0_1698:
	s_or_b64 exec, exec, s[4:5]
	s_waitcnt vmcnt(3)
	v_mov_b32_e32 v52, v29
	s_waitcnt vmcnt(2)
	v_mov_b32_e32 v53, v25
	v_mov_b32_e32 v50, v28
	v_mov_b32_e32 v51, v24
	v_pk_mul_f32 v[52:53], v[52:53], v[52:53]
	s_waitcnt vmcnt(1)
	v_mov_b32_e32 v54, v21
	v_pk_fma_f32 v[50:51], v[50:51], v[50:51], v[52:53]
	v_mov_b32_e32 v52, v30
	v_mov_b32_e32 v53, v26
	v_pk_fma_f32 v[50:51], v[52:53], v[52:53], v[50:51]
	v_mov_b32_e32 v52, v31
	v_mov_b32_e32 v53, v27
	s_waitcnt vmcnt(0)
	v_mov_b32_e32 v55, v17
	v_pk_fma_f32 v[50:51], v[52:53], v[52:53], v[50:51]
	v_mov_b32_e32 v52, v20
	v_mov_b32_e32 v53, v16
	v_pk_mul_f32 v[54:55], v[54:55], v[54:55]
	v_add_f32_e32 v40, v50, v51
	v_pk_fma_f32 v[52:53], v[52:53], v[52:53], v[54:55]
	v_mov_b32_e32 v54, v22
	v_mov_b32_e32 v55, v18
	v_pk_fma_f32 v[52:53], v[54:55], v[54:55], v[52:53]
	v_mov_b32_e32 v54, v23
	v_mov_b32_e32 v55, v19
	v_pk_fma_f32 v[52:53], v[54:55], v[54:55], v[52:53]
	v_lshlrev_b64 v[42:43], 11, v[42:43]
	v_add_f32_e32 v40, v40, v52
	v_add_f32_e32 v40, v40, v53
	s_nop 1
	v_mov_b32_e32 v50, v56
	v_mov_b32_e32 v51, v57
	v_mov_b32_e32 v52, v58
	v_mov_b32_e32 v53, v59
	ds_bpermute_b32 v49, v41, v40
	v_lshl_add_u64 v[42:43], v[36:37], 0, v[42:43]
	s_waitcnt lgkmcnt(0)
	v_add_f32_e32 v40, v40, v49
	ds_bpermute_b32 v49, v44, v40
	s_waitcnt lgkmcnt(0)
	v_add_f32_e32 v40, v40, v49
	ds_bpermute_b32 v49, v45, v40
	s_waitcnt lgkmcnt(0)
	v_add_f32_e32 v40, v40, v49
	ds_bpermute_b32 v49, v46, v40
	s_waitcnt lgkmcnt(0)
	v_add_f32_e32 v40, v40, v49
	ds_bpermute_b32 v49, v47, v40
	s_waitcnt lgkmcnt(0)
	v_add_f32_e32 v40, v40, v49
	ds_bpermute_b32 v49, v48, v40
	s_waitcnt lgkmcnt(0)
	v_add_f32_e32 v40, v40, v49
	v_fmamk_f32 v40, v40, 0x3a800000, v252
	v_cmp_gt_f32_e64 s[4:5], s90, v40
	v_mul_f32_e32 v49, 0x4b800000, v40
	v_pk_mul_f32 v[30:31], v[30:31], v[52:53]
	v_cndmask_b32_e64 v40, v40, v49, s[4:5]
	v_rsq_f32_e32 v40, v40
	v_pk_mul_f32 v[28:29], v[28:29], v[50:51]
	v_mul_f32_e32 v49, 0x45800000, v40
	v_cndmask_b32_e64 v40, v40, v49, s[4:5]
	v_pk_mul_f32 v[30:31], v[30:31], v[40:41] op_sel_hi:[1,0]
	v_pk_mul_f32 v[28:29], v[28:29], v[40:41] op_sel_hi:[1,0]
	s_nop 0
	v_cvt_pk_bf16_f32 v28, v28, v29
	v_cvt_pk_bf16_f32 v29, v30, v31
	global_store_dwordx2 v[42:43], v[28:29], off
	s_nop 1
	v_mov_b32_e32 v28, v60
	v_mov_b32_e32 v29, v61
	v_mov_b32_e32 v30, v62
	v_mov_b32_e32 v31, v63
	v_pk_mul_f32 v[26:27], v[26:27], v[30:31]
	v_pk_mul_f32 v[24:25], v[24:25], v[28:29]
	v_pk_mul_f32 v[26:27], v[26:27], v[40:41] op_sel_hi:[1,0]
	v_pk_mul_f32 v[24:25], v[24:25], v[40:41] op_sel_hi:[1,0]
	s_nop 0
	v_cvt_pk_bf16_f32 v24, v24, v25
	v_cvt_pk_bf16_f32 v25, v26, v27
	global_store_dwordx2 v[42:43], v[24:25], off offset:512
	s_nop 1
	v_mov_b32_e32 v24, v64
	v_mov_b32_e32 v25, v65
	v_mov_b32_e32 v26, v66
	v_mov_b32_e32 v27, v67
	v_pk_mul_f32 v[22:23], v[22:23], v[26:27]
	v_pk_mul_f32 v[20:21], v[20:21], v[24:25]
	v_pk_mul_f32 v[22:23], v[22:23], v[40:41] op_sel_hi:[1,0]
	v_pk_mul_f32 v[20:21], v[20:21], v[40:41] op_sel_hi:[1,0]
	s_nop 0
	v_cvt_pk_bf16_f32 v20, v20, v21
	v_cvt_pk_bf16_f32 v21, v22, v23
	global_store_dwordx2 v[42:43], v[20:21], off offset:1024
	s_nop 1
	v_mov_b32_e32 v20, v68
	v_mov_b32_e32 v21, v69
	v_mov_b32_e32 v22, v70
	v_mov_b32_e32 v23, v71
	v_pk_mul_f32 v[18:19], v[18:19], v[22:23]
	v_pk_mul_f32 v[16:17], v[16:17], v[20:21]
	v_pk_mul_f32 v[18:19], v[18:19], v[40:41] op_sel_hi:[1,0]
	v_pk_mul_f32 v[16:17], v[16:17], v[40:41] op_sel_hi:[1,0]
	s_nop 0
	v_cvt_pk_bf16_f32 v16, v16, v17
	v_cvt_pk_bf16_f32 v17, v18, v19
	global_store_dwordx2 v[42:43], v[16:17], off offset:1536
	s_and_saveexec_b64 s[4:5], vcc
	s_cbranch_execz .LBB0_1695
	v_mov_b32_e32 v18, v9
	v_mov_b32_e32 v19, v13
	v_mov_b32_e32 v16, v8
	v_mov_b32_e32 v17, v12
	v_pk_mul_f32 v[18:19], v[18:19], v[18:19]
	v_mov_b32_e32 v20, v1
	v_pk_fma_f32 v[16:17], v[16:17], v[16:17], v[18:19]
	v_mov_b32_e32 v18, v10
	v_mov_b32_e32 v19, v14
	v_pk_fma_f32 v[16:17], v[18:19], v[18:19], v[16:17]
	v_mov_b32_e32 v18, v11
	v_mov_b32_e32 v19, v15
	v_mov_b32_e32 v21, v5
	v_pk_fma_f32 v[16:17], v[18:19], v[18:19], v[16:17]
	v_mov_b32_e32 v18, v0
	v_mov_b32_e32 v19, v4
	v_pk_mul_f32 v[20:21], v[20:21], v[20:21]
	v_add_f32_e32 v16, v16, v17
	v_pk_fma_f32 v[18:19], v[18:19], v[18:19], v[20:21]
	v_mov_b32_e32 v20, v2
	v_mov_b32_e32 v21, v6
	v_pk_fma_f32 v[18:19], v[20:21], v[20:21], v[18:19]
	v_mov_b32_e32 v20, v3
	v_mov_b32_e32 v21, v7
	v_pk_fma_f32 v[18:19], v[20:21], v[20:21], v[18:19]
	s_nop 1
	v_mov_b32_e32 v20, v56
	v_mov_b32_e32 v21, v57
	v_mov_b32_e32 v22, v58
	v_mov_b32_e32 v23, v59
	v_add_f32_e32 v16, v19, v16
	v_add_f32_e32 v16, v18, v16
	ds_bpermute_b32 v17, v41, v16
	v_lshlrev_b64 v[18:19], 11, v[38:39]
	s_waitcnt lgkmcnt(0)
	v_add_f32_e32 v16, v16, v17
	ds_bpermute_b32 v17, v44, v16
	s_waitcnt lgkmcnt(0)
	v_add_f32_e32 v16, v16, v17
	ds_bpermute_b32 v17, v45, v16
	s_waitcnt lgkmcnt(0)
	v_add_f32_e32 v16, v16, v17
	ds_bpermute_b32 v17, v46, v16
	s_waitcnt lgkmcnt(0)
	v_add_f32_e32 v16, v16, v17
	ds_bpermute_b32 v17, v47, v16
	s_waitcnt lgkmcnt(0)
	v_add_f32_e32 v16, v16, v17
	ds_bpermute_b32 v17, v48, v16
	s_waitcnt lgkmcnt(0)
	v_add_f32_e32 v16, v16, v17
	v_fmamk_f32 v16, v16, 0x3a800000, v252
	v_cmp_gt_f32_e32 vcc, s90, v16
	v_mul_f32_e32 v17, 0x4b800000, v16
	v_pk_mul_f32 v[22:23], v[14:15], v[22:23]
	v_cndmask_b32_e32 v16, v16, v17, vcc
	v_rsq_f32_e32 v16, v16
	v_pk_mul_f32 v[20:21], v[12:13], v[20:21]
	v_mul_f32_e32 v17, 0x45800000, v16
	v_cndmask_b32_e32 v16, v16, v17, vcc
	v_pk_mul_f32 v[22:23], v[22:23], v[16:17] op_sel_hi:[1,0]
	v_pk_mul_f32 v[20:21], v[20:21], v[16:17] op_sel_hi:[1,0]
	s_nop 0
	v_cvt_pk_bf16_f32 v20, v20, v21
	v_cvt_pk_bf16_f32 v21, v22, v23
	v_lshl_add_u64 v[22:23], v[36:37], 0, v[18:19]
	global_store_dwordx2 v[22:23], v[20:21], off
	s_nop 1
	v_mov_b32_e32 v18, v60
	v_mov_b32_e32 v19, v61
	v_mov_b32_e32 v20, v62
	v_mov_b32_e32 v21, v63
	v_pk_mul_f32 v[20:21], v[10:11], v[20:21]
	v_pk_mul_f32 v[18:19], v[8:9], v[18:19]
	v_pk_mul_f32 v[20:21], v[20:21], v[16:17] op_sel_hi:[1,0]
	v_pk_mul_f32 v[18:19], v[18:19], v[16:17] op_sel_hi:[1,0]
	s_nop 0
	v_cvt_pk_bf16_f32 v18, v18, v19
	v_cvt_pk_bf16_f32 v19, v20, v21
	global_store_dwordx2 v[22:23], v[18:19], off offset:512
	s_nop 1
	v_mov_b32_e32 v18, v64
	v_mov_b32_e32 v19, v65
	v_mov_b32_e32 v20, v66
	v_mov_b32_e32 v21, v67
	v_pk_mul_f32 v[20:21], v[6:7], v[20:21]
	v_pk_mul_f32 v[18:19], v[4:5], v[18:19]
	v_pk_mul_f32 v[20:21], v[20:21], v[16:17] op_sel_hi:[1,0]
	v_pk_mul_f32 v[18:19], v[18:19], v[16:17] op_sel_hi:[1,0]
	s_nop 0
	v_cvt_pk_bf16_f32 v18, v18, v19
	v_cvt_pk_bf16_f32 v19, v20, v21
	global_store_dwordx2 v[22:23], v[18:19], off offset:1024
	s_nop 1
	v_mov_b32_e32 v18, v68
	v_mov_b32_e32 v19, v69
	v_mov_b32_e32 v20, v70
	v_mov_b32_e32 v21, v71
	v_pk_mul_f32 v[20:21], v[2:3], v[20:21]
	v_pk_mul_f32 v[18:19], v[0:1], v[18:19]
	v_pk_mul_f32 v[20:21], v[20:21], v[16:17] op_sel_hi:[1,0]
	v_pk_mul_f32 v[16:17], v[18:19], v[16:17] op_sel_hi:[1,0]
	s_nop 0
	v_cvt_pk_bf16_f32 v16, v16, v17
	v_cvt_pk_bf16_f32 v17, v20, v21
	global_store_dwordx2 v[22:23], v[16:17], off offset:1536
	s_branch .LBB0_1695

.LBB0_1944:
	s_mov_b64 s[2:3], s[40:41]
	v_readlane_b32 s4, v255, 24
	s_waitcnt vmcnt(0) lgkmcnt(0)
	v_mov_b64_e32 v[0:1], s[2:3]
	flat_load_dwordx2 v[42:43], v[0:1] offset:248
	s_cmp_lg_u32 s4, 0
	s_cbranch_scc0 .LBB0_1956
	v_mov_b64_e32 v[0:1], s[2:3]
	flat_load_dwordx4 v[0:3], v[0:1] offset:232
	v_mov_b32_e32 v5, v160
	v_readlane_b32 s4, v253, 0
	s_lshl_b32 s4, s4, 3
	v_ashrrev_i32_e32 v4, 6, v5
	v_add_u32_e32 v4, s4, v4
	s_mov_b32 s14, 0x8100
	v_cmp_gt_i32_e32 vcc, s14, v4
	s_and_saveexec_b64 s[6:7], vcc
	s_mov_b32 s15, 0x80ff
	s_cbranch_execz .LBB0_1955
	v_lshlrev_b32_e32 v5, 2, v5
	v_and_b32_e32 v6, 64, v194
	v_and_b32_e32 v36, 0xfc, v5
	v_add_u32_e32 v5, 64, v6
	v_xor_b32_e32 v6, 1, v194
	v_cmp_lt_i32_e32 vcc, v6, v5
	v_readlane_b32 s4, v253, 1
	v_readlane_b32 s5, v253, 2
	v_cndmask_b32_e32 v6, v194, v6, vcc
	v_lshlrev_b32_e32 v37, 2, v6
	v_xor_b32_e32 v6, 2, v194
	v_cmp_lt_i32_e32 vcc, v6, v5
	s_load_dword s4, s[4:5], 0x0
	v_lshlrev_b32_e32 v162, 2, v36
	v_cndmask_b32_e32 v6, v194, v6, vcc
	v_lshlrev_b32_e32 v46, 2, v6
	v_xor_b32_e32 v6, 4, v194
	v_cmp_lt_i32_e32 vcc, v6, v5
	s_waitcnt lgkmcnt(0)
	s_lshl_b32 s12, s4, 3
	s_waitcnt vmcnt(0)
	v_lshl_add_u64 v[0:1], v[0:1], 0, v[162:163]
	v_cndmask_b32_e32 v6, v194, v6, vcc
	v_lshlrev_b32_e32 v47, 2, v6
	v_xor_b32_e32 v6, 8, v194
	v_cmp_lt_i32_e32 vcc, v6, v5
	v_lshl_add_u64 v[38:39], v[42:43], 0, v[162:163]
	v_add_u32_e32 v51, 0xffffff80, v4
	v_cndmask_b32_e32 v6, v194, v6, vcc
	v_lshlrev_b32_e32 v48, 2, v6
	v_xor_b32_e32 v6, 16, v194
	v_cmp_lt_i32_e32 vcc, v6, v5
	s_lshl_b32 s13, s4, 4
	s_mov_b64 s[8:9], 0
	v_cndmask_b32_e32 v6, v194, v6, vcc
	v_lshlrev_b32_e32 v49, 2, v6
	v_xor_b32_e32 v6, 32, v194
	v_cmp_lt_i32_e32 vcc, v6, v5
	s_nop 1
	v_cndmask_b32_e32 v5, v194, v6, vcc
	v_lshlrev_b32_e32 v50, 2, v5
	global_load_dwordx4 v[60:63], v[0:1], off
	global_load_dwordx4 v[64:67], v[0:1], off offset:1024
	global_load_dwordx4 v[68:71], v[0:1], off offset:2048
	global_load_dwordx4 v[72:75], v[0:1], off offset:3072
	s_waitcnt vmcnt(0)
	s_branch .LBB0_1948

.LBB0_1950:
	s_or_b64 exec, exec, s[4:5]
	s_waitcnt vmcnt(3)
	v_mul_f32_e32 v41, v33, v33
	s_waitcnt vmcnt(2)
	v_mul_f32_e32 v45, v29, v29
	v_fmac_f32_e32 v41, v32, v32
	v_fmac_f32_e32 v45, v28, v28
	v_fmac_f32_e32 v41, v34, v34
	v_fmac_f32_e32 v45, v30, v30
	v_fmac_f32_e32 v41, v35, v35
	v_fmac_f32_e32 v45, v31, v31
	v_add_f32_e32 v41, v41, v45
	s_waitcnt vmcnt(1)
	v_mul_f32_e32 v45, v25, v25
	v_fmac_f32_e32 v45, v24, v24
	v_fmac_f32_e32 v45, v26, v26
	v_fmac_f32_e32 v45, v27, v27
	v_add_f32_e32 v41, v41, v45
	s_waitcnt vmcnt(0)
	v_mul_f32_e32 v45, v21, v21
	v_fmac_f32_e32 v45, v20, v20
	v_fmac_f32_e32 v45, v22, v22
	v_fmac_f32_e32 v45, v23, v23
	v_add_f32_e32 v41, v41, v45
	ds_bpermute_b32 v45, v37, v41
	s_mov_b32 s4, 0xfe03f81
	v_mul_hi_i32 v44, v44, s4
	v_lshrrev_b32_e32 v53, 31, v44
	v_ashrrev_i32_e32 v44, 10, v44
	s_waitcnt lgkmcnt(0)
	v_add_f32_e32 v41, v41, v45
	ds_bpermute_b32 v45, v46, v41
	v_add_u32_e32 v44, v44, v53
	s_movk_i32 s4, 0xbf80
	v_mad_i32_i24 v162, v44, s4, v51
	s_movk_i32 s4, 0x7f
	s_waitcnt lgkmcnt(0)
	v_add_f32_e32 v41, v41, v45
	ds_bpermute_b32 v45, v47, v41
	s_waitcnt lgkmcnt(0)
	v_add_f32_e32 v41, v41, v45
	ds_bpermute_b32 v45, v48, v41
	s_waitcnt lgkmcnt(0)
	v_add_f32_e32 v41, v41, v45
	ds_bpermute_b32 v45, v49, v41
	s_waitcnt lgkmcnt(0)
	v_add_f32_e32 v41, v41, v45
	ds_bpermute_b32 v52, v50, v41
	v_add_u32_e32 v45, 0x80, v162
	v_cmp_lt_i32_e64 s[4:5], s4, v45
	s_and_saveexec_b64 s[10:11], s[4:5]
	s_cbranch_execz .LBB0_1952
	s_waitcnt lgkmcnt(0)
	v_add_f32_e32 v41, v41, v52
	v_fmamk_f32 v41, v41, 0x3a800000, v252
	v_cmp_gt_f32_e64 s[4:5], s90, v41
	v_mul_f32_e32 v52, 0x4b800000, v41
	v_ashrrev_i32_e32 v45, 31, v44
	v_cndmask_b32_e64 v41, v41, v52, s[4:5]
	v_rsq_f32_e32 v41, v41
	v_lshlrev_b64 v[44:45], 26, v[44:45]
	v_lshl_add_u64 v[44:45], v[2:3], 0, v[44:45]
	v_lshlrev_b64 v[54:55], 12, v[162:163]
	v_mul_f32_e32 v52, 0x45800000, v41
	v_lshl_add_u64 v[44:45], v[44:45], 0, v[54:55]
	v_cndmask_b32_e64 v56, v41, v52, s[4:5]
	s_nop 1
	v_mov_b32_e32 v52, v60
	v_mov_b32_e32 v53, v61
	v_mov_b32_e32 v54, v62
	v_mov_b32_e32 v55, v63
	v_lshlrev_b32_e32 v162, 2, v36
	v_lshl_add_u64 v[44:45], v[44:45], 0, v[162:163]
	v_pk_mul_f32 v[34:35], v[34:35], v[54:55]
	v_pk_mul_f32 v[32:33], v[32:33], v[52:53]
	v_pk_mul_f32 v[34:35], v[56:57], v[34:35] op_sel_hi:[0,1]
	v_pk_mul_f32 v[32:33], v[56:57], v[32:33] op_sel_hi:[0,1]
	global_store_dwordx4 v[44:45], v[32:35], off
	s_nop 1
	v_mov_b32_e32 v32, v64
	v_mov_b32_e32 v33, v65
	v_mov_b32_e32 v34, v66
	v_mov_b32_e32 v35, v67
	v_pk_mul_f32 v[30:31], v[30:31], v[34:35]
	v_pk_mul_f32 v[28:29], v[28:29], v[32:33]
	v_pk_mul_f32 v[30:31], v[56:57], v[30:31] op_sel_hi:[0,1]
	v_pk_mul_f32 v[28:29], v[56:57], v[28:29] op_sel_hi:[0,1]
	global_store_dwordx4 v[44:45], v[28:31], off offset:1024
	s_nop 1
	v_mov_b32_e32 v28, v68
	v_mov_b32_e32 v29, v69
	v_mov_b32_e32 v30, v70
	v_mov_b32_e32 v31, v71
	v_pk_mul_f32 v[26:27], v[26:27], v[30:31]
	v_pk_mul_f32 v[24:25], v[24:25], v[28:29]
	v_pk_mul_f32 v[26:27], v[56:57], v[26:27] op_sel_hi:[0,1]
	v_pk_mul_f32 v[24:25], v[56:57], v[24:25] op_sel_hi:[0,1]
	global_store_dwordx4 v[44:45], v[24:27], off offset:2048
	s_nop 1
	v_mov_b32_e32 v24, v72
	v_mov_b32_e32 v25, v73
	v_mov_b32_e32 v26, v74
	v_mov_b32_e32 v27, v75
	v_pk_mul_f32 v[22:23], v[22:23], v[26:27]
	v_pk_mul_f32 v[20:21], v[20:21], v[24:25]
	v_pk_mul_f32 v[22:23], v[56:57], v[22:23] op_sel_hi:[0,1]
	v_pk_mul_f32 v[20:21], v[56:57], v[20:21] op_sel_hi:[0,1]
	global_store_dwordx4 v[44:45], v[20:23], off offset:3072
.LBB0_1952:
	s_or_b64 exec, exec, s[10:11]
	s_and_saveexec_b64 s[4:5], vcc
	s_cbranch_execz .LBB0_1947
	v_mul_f32_e32 v20, v17, v17
	v_mul_f32_e32 v21, v13, v13
	v_fmac_f32_e32 v20, v16, v16
	v_fmac_f32_e32 v21, v12, v12
	v_fmac_f32_e32 v20, v18, v18
	v_fmac_f32_e32 v21, v14, v14
	v_fmac_f32_e32 v20, v19, v19
	v_fmac_f32_e32 v21, v15, v15
	v_add_f32_e32 v20, v21, v20
	v_mul_f32_e32 v21, v9, v9
	v_fmac_f32_e32 v21, v8, v8
	v_fmac_f32_e32 v21, v10, v10
	v_fmac_f32_e32 v21, v11, v11
	v_add_f32_e32 v20, v21, v20
	v_mul_f32_e32 v21, v5, v5
	v_fmac_f32_e32 v21, v4, v4
	v_fmac_f32_e32 v21, v6, v6
	v_fmac_f32_e32 v21, v7, v7
	v_add_f32_e32 v20, v21, v20
	ds_bpermute_b32 v21, v37, v20
	s_mov_b32 s10, 0xfe03f81
	s_waitcnt lgkmcnt(0)
	v_add_f32_e32 v20, v20, v21
	ds_bpermute_b32 v21, v46, v20
	s_waitcnt lgkmcnt(0)
	v_add_f32_e32 v20, v20, v21
	ds_bpermute_b32 v21, v47, v20
	s_waitcnt lgkmcnt(0)
	v_add_f32_e32 v20, v20, v21
	ds_bpermute_b32 v21, v48, v20
	s_waitcnt lgkmcnt(0)
	v_add_f32_e32 v21, v20, v21
	ds_bpermute_b32 v22, v49, v21
	v_mul_hi_i32 v20, v40, s10
	v_lshrrev_b32_e32 v23, 31, v20
	v_ashrrev_i32_e32 v20, 10, v20
	v_add_u32_e32 v20, v20, v23
	s_waitcnt lgkmcnt(0)
	v_add_f32_e32 v22, v21, v22
	ds_bpermute_b32 v23, v50, v22
	v_mul_i32_i24_e32 v21, 0xffffbf80, v20
	v_add3_u32 v162, s12, v21, v51
	v_add_u32_e32 v21, 0x80, v162
	s_movk_i32 s10, 0x7f
	v_cmp_lt_i32_e32 vcc, s10, v21
	s_and_b64 exec, exec, vcc
	s_cbranch_execz .LBB0_1947
	v_ashrrev_i32_e32 v21, 31, v20
	v_lshlrev_b64 v[20:21], 26, v[20:21]
	v_lshl_add_u64 v[20:21], v[2:3], 0, v[20:21]
	v_lshlrev_b64 v[24:25], 12, v[162:163]
	v_lshl_add_u64 v[24:25], v[20:21], 0, v[24:25]
	s_waitcnt lgkmcnt(0)
	v_add_f32_e32 v20, v22, v23
	v_fmamk_f32 v20, v20, 0x3a800000, v252
	v_cmp_gt_f32_e32 vcc, s90, v20
	v_mul_f32_e32 v21, 0x4b800000, v20
	v_lshlrev_b32_e32 v162, 2, v36
	v_cndmask_b32_e32 v20, v20, v21, vcc
	v_rsq_f32_e32 v20, v20
	v_lshl_add_u64 v[24:25], v[24:25], 0, v[162:163]
	v_mul_f32_e32 v21, 0x45800000, v20
	v_cndmask_b32_e32 v26, v20, v21, vcc
	s_nop 1
	v_mov_b32_e32 v20, v60
	v_mov_b32_e32 v21, v61
	v_mov_b32_e32 v22, v62
	v_mov_b32_e32 v23, v63
	v_pk_mul_f32 v[22:23], v[18:19], v[22:23]
	v_pk_mul_f32 v[20:21], v[16:17], v[20:21]
	v_pk_mul_f32 v[22:23], v[26:27], v[22:23] op_sel_hi:[0,1]
	v_pk_mul_f32 v[20:21], v[26:27], v[20:21] op_sel_hi:[0,1]
	global_store_dwordx4 v[24:25], v[20:23], off
	s_nop 1
	v_mov_b32_e32 v20, v64
	v_mov_b32_e32 v21, v65
	v_mov_b32_e32 v22, v66
	v_mov_b32_e32 v23, v67
	v_pk_mul_f32 v[22:23], v[14:15], v[22:23]
	v_pk_mul_f32 v[20:21], v[12:13], v[20:21]
	v_pk_mul_f32 v[22:23], v[26:27], v[22:23] op_sel_hi:[0,1]
	v_pk_mul_f32 v[20:21], v[26:27], v[20:21] op_sel_hi:[0,1]
	global_store_dwordx4 v[24:25], v[20:23], off offset:1024
	s_nop 1
	v_mov_b32_e32 v20, v68
	v_mov_b32_e32 v21, v69
	v_mov_b32_e32 v22, v70
	v_mov_b32_e32 v23, v71
	v_pk_mul_f32 v[22:23], v[10:11], v[22:23]
	v_pk_mul_f32 v[20:21], v[8:9], v[20:21]
	v_pk_mul_f32 v[22:23], v[26:27], v[22:23] op_sel_hi:[0,1]
	v_pk_mul_f32 v[20:21], v[26:27], v[20:21] op_sel_hi:[0,1]
	global_store_dwordx4 v[24:25], v[20:23], off offset:2048
	s_nop 1
	v_mov_b32_e32 v20, v72
	v_mov_b32_e32 v21, v73
	v_mov_b32_e32 v22, v74
	v_mov_b32_e32 v23, v75
	v_pk_mul_f32 v[22:23], v[6:7], v[22:23]
	v_pk_mul_f32 v[20:21], v[4:5], v[20:21]
	v_pk_mul_f32 v[22:23], v[26:27], v[22:23] op_sel_hi:[0,1]
	v_pk_mul_f32 v[20:21], v[26:27], v[20:21] op_sel_hi:[0,1]
	global_store_dwordx4 v[24:25], v[20:23], off offset:3072
	s_branch .LBB0_1947

.LBB0_1957:
	s_waitcnt vmcnt(0) lgkmcnt(0)
	v_mov_b64_e32 v[0:1], s[2:3]
	flat_load_dwordx2 v[0:1], v[0:1] offset:16
	v_mov_b32_e32 v2, v160
	v_readlane_b32 s2, v253, 0
	v_ashrrev_i32_e32 v3, 6, v2
	s_nop 0
	v_lshl_add_u32 v48, s2, 3, v3
	v_cmp_gt_i32_e32 vcc, s14, v48
	s_and_saveexec_b64 s[2:3], vcc
	s_cbranch_execz .LBB0_1964
	v_lshlrev_b32_e32 v2, 2, v2
	v_and_b32_e32 v3, 64, v194
	v_and_b32_e32 v4, 0xfc, v2
	v_add_u32_e32 v2, 64, v3
	v_xor_b32_e32 v3, 1, v194
	v_cmp_lt_i32_e32 vcc, v3, v2
	v_readlane_b32 s4, v253, 1
	v_readlane_b32 s5, v253, 2
	v_cndmask_b32_e32 v3, v194, v3, vcc
	v_lshlrev_b32_e32 v47, 2, v3
	v_xor_b32_e32 v3, 2, v194
	v_cmp_lt_i32_e32 vcc, v3, v2
	s_load_dword s6, s[4:5], 0x0
	s_mov_b64 s[4:5], 0x1000
	v_cndmask_b32_e32 v3, v194, v3, vcc
	v_lshlrev_b32_e32 v50, 2, v3
	v_xor_b32_e32 v3, 4, v194
	v_cmp_lt_i32_e32 vcc, v3, v2
	v_lshlrev_b32_e32 v162, 2, v4
	s_waitcnt vmcnt(0) lgkmcnt(0)
	v_lshl_add_u64 v[0:1], v[0:1], 0, s[4:5]
	v_cndmask_b32_e32 v3, v194, v3, vcc
	v_lshlrev_b32_e32 v51, 2, v3
	v_xor_b32_e32 v3, 8, v194
	v_cmp_lt_i32_e32 vcc, v3, v2
	v_lshl_add_u64 v[32:33], v[0:1], 0, v[162:163]
	v_lshl_add_u64 v[40:41], v[42:43], 0, v[162:163]
	v_cndmask_b32_e32 v3, v194, v3, vcc
	v_lshlrev_b32_e32 v52, 2, v3
	v_xor_b32_e32 v3, 16, v194
	v_cmp_lt_i32_e32 vcc, v3, v2
	s_mov_b64 s[4:5], 0x8100000
	s_lshl_b32 s8, s6, 3
	v_cndmask_b32_e32 v3, v194, v3, vcc
	v_lshlrev_b32_e32 v53, 2, v3
	v_xor_b32_e32 v3, 32, v194
	v_cmp_lt_i32_e32 vcc, v3, v2
	s_mov_b64 s[6:7], 0
	s_nop 0
	v_cndmask_b32_e32 v2, v194, v3, vcc
	v_lshlrev_b32_e32 v54, 2, v2
	v_or_b32_e32 v2, 0x400, v162
	v_mov_b32_e32 v3, v163
	v_lshl_add_u64 v[34:35], v[0:1], 0, v[2:3]
	v_or_b32_e32 v2, 0x800, v162
	v_lshl_add_u64 v[36:37], v[0:1], 0, v[2:3]
	v_or_b32_e32 v2, 0xc00, v162
	v_lshlrev_b32_e32 v162, 1, v4
	v_lshl_add_u64 v[38:39], v[0:1], 0, v[2:3]
	v_lshl_add_u64 v[0:1], v[42:43], 0, v[162:163]
	v_lshl_add_u64 v[42:43], v[0:1], 0, s[4:5]
	global_load_dwordx4 v[76:79], v[32:33], off
	global_load_dwordx4 v[80:83], v[34:35], off
	global_load_dwordx4 v[84:87], v[36:37], off
	global_load_dwordx4 v[88:91], v[38:39], off
	s_waitcnt vmcnt(0)
	s_branch .LBB0_1960

.LBB0_1962:
	s_or_b64 exec, exec, s[4:5]
	s_waitcnt vmcnt(3)
	v_mov_b32_e32 v58, v29
	s_waitcnt vmcnt(2)
	v_mov_b32_e32 v59, v25
	v_mov_b32_e32 v56, v28
	v_mov_b32_e32 v57, v24
	v_pk_mul_f32 v[58:59], v[58:59], v[58:59]
	s_waitcnt vmcnt(1)
	v_mov_b32_e32 v60, v21
	v_pk_fma_f32 v[56:57], v[56:57], v[56:57], v[58:59]
	v_mov_b32_e32 v58, v30
	v_mov_b32_e32 v59, v26
	v_pk_fma_f32 v[56:57], v[58:59], v[58:59], v[56:57]
	v_mov_b32_e32 v58, v31
	v_mov_b32_e32 v59, v27
	s_waitcnt vmcnt(0)
	v_mov_b32_e32 v61, v17
	v_pk_fma_f32 v[56:57], v[58:59], v[58:59], v[56:57]
	v_mov_b32_e32 v58, v20
	v_mov_b32_e32 v59, v16
	v_pk_mul_f32 v[60:61], v[60:61], v[60:61]
	v_add_f32_e32 v46, v56, v57
	v_pk_fma_f32 v[58:59], v[58:59], v[58:59], v[60:61]
	v_mov_b32_e32 v60, v22
	v_mov_b32_e32 v61, v18
	v_pk_fma_f32 v[58:59], v[60:61], v[60:61], v[58:59]
	v_mov_b32_e32 v60, v23
	v_mov_b32_e32 v61, v19
	v_pk_fma_f32 v[58:59], v[60:61], v[60:61], v[58:59]
	v_lshlrev_b64 v[48:49], 11, v[48:49]
	v_add_f32_e32 v46, v46, v58
	v_add_f32_e32 v46, v46, v59
	s_nop 1
	v_mov_b32_e32 v56, v76
	v_mov_b32_e32 v57, v77
	v_mov_b32_e32 v58, v78
	v_mov_b32_e32 v59, v79
	ds_bpermute_b32 v55, v47, v46
	v_lshl_add_u64 v[48:49], v[42:43], 0, v[48:49]
	s_waitcnt lgkmcnt(0)
	v_add_f32_e32 v46, v46, v55
	ds_bpermute_b32 v55, v50, v46
	s_waitcnt lgkmcnt(0)
	v_add_f32_e32 v46, v46, v55
	ds_bpermute_b32 v55, v51, v46
	s_waitcnt lgkmcnt(0)
	v_add_f32_e32 v46, v46, v55
	ds_bpermute_b32 v55, v52, v46
	s_waitcnt lgkmcnt(0)
	v_add_f32_e32 v46, v46, v55
	ds_bpermute_b32 v55, v53, v46
	s_waitcnt lgkmcnt(0)
	v_add_f32_e32 v46, v46, v55
	ds_bpermute_b32 v55, v54, v46
	s_waitcnt lgkmcnt(0)
	v_add_f32_e32 v46, v46, v55
	v_fmamk_f32 v46, v46, 0x3a800000, v252
	v_cmp_gt_f32_e64 s[4:5], s90, v46
	v_mul_f32_e32 v55, 0x4b800000, v46
	v_pk_mul_f32 v[30:31], v[30:31], v[58:59]
	v_cndmask_b32_e64 v46, v46, v55, s[4:5]
	v_rsq_f32_e32 v46, v46
	v_pk_mul_f32 v[28:29], v[28:29], v[56:57]
	v_mul_f32_e32 v55, 0x45800000, v46
	v_cndmask_b32_e64 v46, v46, v55, s[4:5]
	v_pk_mul_f32 v[30:31], v[30:31], v[46:47] op_sel_hi:[1,0]
	v_pk_mul_f32 v[28:29], v[28:29], v[46:47] op_sel_hi:[1,0]
	s_nop 0
	v_cvt_pk_bf16_f32 v28, v28, v29
	v_cvt_pk_bf16_f32 v29, v30, v31
	global_store_dwordx2 v[48:49], v[28:29], off
	s_nop 1
	v_mov_b32_e32 v28, v80
	v_mov_b32_e32 v29, v81
	v_mov_b32_e32 v30, v82
	v_mov_b32_e32 v31, v83
	v_pk_mul_f32 v[26:27], v[26:27], v[30:31]
	v_pk_mul_f32 v[24:25], v[24:25], v[28:29]
	v_pk_mul_f32 v[26:27], v[26:27], v[46:47] op_sel_hi:[1,0]
	v_pk_mul_f32 v[24:25], v[24:25], v[46:47] op_sel_hi:[1,0]
	s_nop 0
	v_cvt_pk_bf16_f32 v24, v24, v25
	v_cvt_pk_bf16_f32 v25, v26, v27
	global_store_dwordx2 v[48:49], v[24:25], off offset:512
	s_nop 1
	v_mov_b32_e32 v24, v84
	v_mov_b32_e32 v25, v85
	v_mov_b32_e32 v26, v86
	v_mov_b32_e32 v27, v87
	v_pk_mul_f32 v[22:23], v[22:23], v[26:27]
	v_pk_mul_f32 v[20:21], v[20:21], v[24:25]
	v_pk_mul_f32 v[22:23], v[22:23], v[46:47] op_sel_hi:[1,0]
	v_pk_mul_f32 v[20:21], v[20:21], v[46:47] op_sel_hi:[1,0]
	s_nop 0
	v_cvt_pk_bf16_f32 v20, v20, v21
	v_cvt_pk_bf16_f32 v21, v22, v23
	global_store_dwordx2 v[48:49], v[20:21], off offset:1024
	s_nop 1
	v_mov_b32_e32 v20, v88
	v_mov_b32_e32 v21, v89
	v_mov_b32_e32 v22, v90
	v_mov_b32_e32 v23, v91
	v_pk_mul_f32 v[18:19], v[18:19], v[22:23]
	v_pk_mul_f32 v[16:17], v[16:17], v[20:21]
	v_pk_mul_f32 v[18:19], v[18:19], v[46:47] op_sel_hi:[1,0]
	v_pk_mul_f32 v[16:17], v[16:17], v[46:47] op_sel_hi:[1,0]
	s_nop 0
	v_cvt_pk_bf16_f32 v16, v16, v17
	v_cvt_pk_bf16_f32 v17, v18, v19
	global_store_dwordx2 v[48:49], v[16:17], off offset:1536
	s_and_saveexec_b64 s[4:5], vcc
	s_cbranch_execz .LBB0_1959
	v_mov_b32_e32 v18, v9
	v_mov_b32_e32 v19, v13
	v_mov_b32_e32 v16, v8
	v_mov_b32_e32 v17, v12
	v_pk_mul_f32 v[18:19], v[18:19], v[18:19]
	v_mov_b32_e32 v20, v1
	v_pk_fma_f32 v[16:17], v[16:17], v[16:17], v[18:19]
	v_mov_b32_e32 v18, v10
	v_mov_b32_e32 v19, v14
	v_pk_fma_f32 v[16:17], v[18:19], v[18:19], v[16:17]
	v_mov_b32_e32 v18, v11
	v_mov_b32_e32 v19, v15
	v_mov_b32_e32 v21, v5
	v_pk_fma_f32 v[16:17], v[18:19], v[18:19], v[16:17]
	v_mov_b32_e32 v18, v0
	v_mov_b32_e32 v19, v4
	v_pk_mul_f32 v[20:21], v[20:21], v[20:21]
	v_add_f32_e32 v16, v16, v17
	v_pk_fma_f32 v[18:19], v[18:19], v[18:19], v[20:21]
	v_mov_b32_e32 v20, v2
	v_mov_b32_e32 v21, v6
	v_pk_fma_f32 v[18:19], v[20:21], v[20:21], v[18:19]
	v_mov_b32_e32 v20, v3
	v_mov_b32_e32 v21, v7
	v_pk_fma_f32 v[18:19], v[20:21], v[20:21], v[18:19]
	s_nop 1
	v_mov_b32_e32 v20, v76
	v_mov_b32_e32 v21, v77
	v_mov_b32_e32 v22, v78
	v_mov_b32_e32 v23, v79
	v_add_f32_e32 v16, v19, v16
	v_add_f32_e32 v16, v18, v16
	ds_bpermute_b32 v17, v47, v16
	v_lshlrev_b64 v[18:19], 11, v[44:45]
	s_waitcnt lgkmcnt(0)
	v_add_f32_e32 v16, v16, v17
	ds_bpermute_b32 v17, v50, v16
	s_waitcnt lgkmcnt(0)
	v_add_f32_e32 v16, v16, v17
	ds_bpermute_b32 v17, v51, v16
	s_waitcnt lgkmcnt(0)
	v_add_f32_e32 v16, v16, v17
	ds_bpermute_b32 v17, v52, v16
	s_waitcnt lgkmcnt(0)
	v_add_f32_e32 v16, v16, v17
	ds_bpermute_b32 v17, v53, v16
	s_waitcnt lgkmcnt(0)
	v_add_f32_e32 v16, v16, v17
	ds_bpermute_b32 v17, v54, v16
	s_waitcnt lgkmcnt(0)
	v_add_f32_e32 v16, v16, v17
	v_fmamk_f32 v16, v16, 0x3a800000, v252
	v_cmp_gt_f32_e32 vcc, s90, v16
	v_mul_f32_e32 v17, 0x4b800000, v16
	v_pk_mul_f32 v[22:23], v[14:15], v[22:23]
	v_cndmask_b32_e32 v16, v16, v17, vcc
	v_rsq_f32_e32 v16, v16
	v_pk_mul_f32 v[20:21], v[12:13], v[20:21]
	v_mul_f32_e32 v17, 0x45800000, v16
	v_cndmask_b32_e32 v16, v16, v17, vcc
	v_pk_mul_f32 v[22:23], v[22:23], v[16:17] op_sel_hi:[1,0]
	v_pk_mul_f32 v[20:21], v[20:21], v[16:17] op_sel_hi:[1,0]
	s_nop 0
	v_cvt_pk_bf16_f32 v20, v20, v21
	v_cvt_pk_bf16_f32 v21, v22, v23
	v_lshl_add_u64 v[22:23], v[42:43], 0, v[18:19]
	global_store_dwordx2 v[22:23], v[20:21], off
	s_nop 1
	v_mov_b32_e32 v18, v80
	v_mov_b32_e32 v19, v81
	v_mov_b32_e32 v20, v82
	v_mov_b32_e32 v21, v83
	v_pk_mul_f32 v[20:21], v[10:11], v[20:21]
	v_pk_mul_f32 v[18:19], v[8:9], v[18:19]
	v_pk_mul_f32 v[20:21], v[20:21], v[16:17] op_sel_hi:[1,0]
	v_pk_mul_f32 v[18:19], v[18:19], v[16:17] op_sel_hi:[1,0]
	s_nop 0
	v_cvt_pk_bf16_f32 v18, v18, v19
	v_cvt_pk_bf16_f32 v19, v20, v21
	global_store_dwordx2 v[22:23], v[18:19], off offset:512
	s_nop 1
	v_mov_b32_e32 v18, v84
	v_mov_b32_e32 v19, v85
	v_mov_b32_e32 v20, v86
	v_mov_b32_e32 v21, v87
	v_pk_mul_f32 v[20:21], v[6:7], v[20:21]
	v_pk_mul_f32 v[18:19], v[4:5], v[18:19]
	v_pk_mul_f32 v[20:21], v[20:21], v[16:17] op_sel_hi:[1,0]
	v_pk_mul_f32 v[18:19], v[18:19], v[16:17] op_sel_hi:[1,0]
	s_nop 0
	v_cvt_pk_bf16_f32 v18, v18, v19
	v_cvt_pk_bf16_f32 v19, v20, v21
	global_store_dwordx2 v[22:23], v[18:19], off offset:1024
	s_nop 1
	v_mov_b32_e32 v18, v88
	v_mov_b32_e32 v19, v89
	v_mov_b32_e32 v20, v90
	v_mov_b32_e32 v21, v91
	v_pk_mul_f32 v[20:21], v[2:3], v[20:21]
	v_pk_mul_f32 v[18:19], v[0:1], v[18:19]
	v_pk_mul_f32 v[20:21], v[20:21], v[16:17] op_sel_hi:[1,0]
	v_pk_mul_f32 v[16:17], v[18:19], v[16:17] op_sel_hi:[1,0]
	s_nop 0
	v_cvt_pk_bf16_f32 v16, v16, v17
	v_cvt_pk_bf16_f32 v17, v20, v21
	global_store_dwordx2 v[22:23], v[16:17], off offset:1536
	s_branch .LBB0_1959
